# attention double-buffered staging: all waves stage the next K/V tile after their compute (ATH=8) (on v61)
# baseline (speedup 1.0000x reference)
; #define LAS __attribute__((address_space(3)))
; __device__ __forceinline__ void attn_bh(const Ctx& F, int b, int h) {
;     ...
;         for (int t = 0; t < NT; ++t) {
;             __syncthreads();
;             *(LAS u32x4*)(Kl + (tid >> 3) * KP + (tid & 7) * 16) = kr0;
;             if (tid < 256) *(LAS u32x4*)(Kl + (tid >> 2) * KP + 128 + (tid & 3) * 16) = kr1;
;             { const int kv = tid >> 3, dc = tid & 7;
; #pragma unroll
;               for (int j = 0; j < 4; ++j) { const unsigned wv = vr[j];
;                   *(LAS bf16_t*)(Vl + (8 * dc + 2 * j) * VP + kv * 2) = (bf16_t)(wv & 0xffffu); *(LAS bf16_t*)(Vl + (8 * dc + 2 * j + 1) * VP + kv * 2) = (bf16_t)(wv >> 16); } }
;             __syncthreads();
;             if (t + 1 < NT) { const bf16_t* kn = Kh + (size_t)(t + 1) * 64 * 64; const bf16_t* krn = Krp + (size_t)(t + 1) * 64 * 32; const bf16_t* vn = Vh + (size_t)(t + 1) * 64 * 64;
;                 kr0 = *(const u32x4*)(kn + (size_t)tid * 8); if (tid < 256) kr1 = *(const u32x4*)(krn + (size_t)tid * 8); vr = *(const u32x4*)(vn + (size_t)tid * 8); }
.LBB0_775:
	s_cmp_lt_u32 s50, 8
	s_cbranch_scc1 .Lat_stage

; __device__ __forceinline__ void attn_bh(const Ctx& F, int b, int h) {
;     ...
;             __syncthreads();
;             if (t + 1 < NT) { const bf16_t* kn = Kh + (size_t)(t + 1) * 64 * 64; const bf16_t* krn = Krp + (size_t)(t + 1) * 64 * 32; const bf16_t* vn = Vh + (size_t)(t + 1) * 64 * 64;
;                 kr0 = *(const u32x4*)(kn + (size_t)tid * 8); if (tid < 256) kr1 = *(const u32x4*)(krn + (size_t)tid * 8); vr = *(const u32x4*)(vn + (size_t)tid * 8); }
;             const int kv0 = 64 * t;
;             if (kv0 <= wlast) {
.LBB0_776:
	s_waitcnt lgkmcnt(0)
	s_barrier
	v_add_u32_e32 v174, s60, v126
	v_add_u32_e32 v175, s60, v127
	s_cmp_lt_u32 s50, 8
	s_cbranch_scc1 .LBB0_782
